# strategy 7.11 loop-edge: phase 19 pair loop computes the next pair's LDS-DMA scalar addresses in front of the loop-top wait+barrier; only the DMA instructions follow the barrier
# speedup vs baseline: 1.0125x; 1.0056x over previous
; #define ATT_ISSUE2(p_, st_) do { LAS unsigned char* sp_ = lds + (st_) * STG2; const int ta_ = dual ? (p_) : 2 * (p_), tb_ = dual ? (p_) : 2 * (p_) + 1; ATT_ISSUE1(u, ta_, sp_); ATT_ISSUEM(ta_, sp_ + 2 * STAGEB); \
;         if (dual || tb_ < u.ntiles) { ATT_ISSUE1(ub, tb_, sp_ + STAGEB); ATT_ISSUEM(tb_, sp_ + 2 * STAGEB + MSKB); } } while (0)
; template <int LAYER>
; __device__ __forceinline__ TileSrc tile_src(const Frame& F, const AttnUnit& u, int t, int j) {
;     TileSrc s;
;     if (LAYER == 0) {
;         const bf16* KA = (const bf16*)(F.ws + WS_KA); const bf16* VA = (const bf16*)(F.ws + WS_VA);
;         if (!u.samp) { const size_t o = ((size_t)(u.b * TP + 64 * t) * D + u.head * 128) * 2; s.k = (const char*)KA + o; s.v = (const char*)VA + o; s.ldb = D * 2; s.f32 = 0; }
;         else if (t < 64 && u.cv) { const size_t o = ((((size_t)u.b * PAST + 64 * t) * 16 + u.head) * 128) * 2; s.k = (const char*)(F.ws + WS_KC) + o; s.v = (const char*)(F.ws + WS_VC) + o; s.ldb = D * 2; s.f32 = 0; }
;         else if (t < 64) { const size_t o = ((((size_t)(j * 8 + u.b) * PAST + 64 * t) * 16 + u.head) * 128) * 4; s.k = (const char*)F.a->in[2] + o; s.v = (const char*)F.a->in[3] + o; s.ldb = D * 4; s.f32 = 1; }
;         else { const size_t o = ((size_t)(NP + u.b * TS) * D + u.head * 128) * 2; s.k = (const char*)KA + o; s.v = (const char*)VA + o; s.ldb = D * 2; s.f32 = 0; }
;     ...
;         const AttnUnit& ub = dual ? u2 : u;
;         const int npairs = dual ? u.ntiles : (u.ntiles + 1) >> 1, p0 = dual ? T0 : T0 >> 1;
;         ATT_ISSUE2(p0, p0 & 1);
;         for (int p = p0; p < npairs; ++p) {
;             asm volatile("s_waitcnt vmcnt(0)" ::: "memory");
;             __builtin_amdgcn_s_barrier(); asm volatile("" ::: "memory");
;             if (p + 1 < npairs) ATT_ISSUE2(p + 1, (p + 1) & 1);
.LBB0_3301:
	s_add_i32 s96, s97, 1
	s_cmp_ge_i32 s96, s21
	s_cselect_b64 s[46:47], -1, 0
	s_and_b64 vcc, exec, s[46:47]
	s_cbranch_vccnz .Lpb19_done
	s_mov_b64 s[48:49], -1
	s_and_b64 vcc, exec, s[26:27]
	s_cbranch_vccz .Lpb19_a2
	s_cmp_gt_u32 s97, 62
	s_mov_b64 s[4:5], s[38:39]
	s_mov_b64 s[2:3], s[36:37]
	s_cbranch_scc1 .Lpb19_a1
	s_add_i32 s2, s90, s95
	s_or_b32 s2, s34, s2
	s_mov_b32 s3, s35
	s_lshl_b64 s[4:5], s[2:3], 8
	s_add_u32 s2, s62, s4
	s_addc_u32 s3, s63, s5
	s_add_u32 s4, s70, s4
	s_addc_u32 s5, s71, s5

; template <int LAYER>
; __device__ __forceinline__ TileSrc tile_src(const Frame& F, const AttnUnit& u, int t, int j) {
;     ...
;         else if (t < 64 && u.cv) { const size_t o = ((((size_t)u.b * PAST + 64 * t) * 16 + u.head) * 128) * 2; s.k = (const char*)(F.ws + WS_KC) + o; s.v = (const char*)(F.ws + WS_VC) + o; s.ldb = D * 2; s.f32 = 0; }
;         else if (t < 64) { const size_t o = ((((size_t)(j * 8 + u.b) * PAST + 64 * t) * 16 + u.head) * 128) * 4; s.k = (const char*)F.a->in[2] + o; s.v = (const char*)F.a->in[3] + o; s.ldb = D * 4; s.f32 = 1; }
;         else { const size_t o = ((size_t)(NP + u.b * TS) * D + u.head * 128) * 2; s.k = (const char*)KA + o; s.v = (const char*)VA + o; s.ldb = D * 2; s.f32 = 0; }
.Lpb19_a3:
	s_mov_b64 s[48:49], -1
	s_and_b64 vcc, exec, s[26:27]
	s_cbranch_vccz .Lpb19_b2
	s_cmp_gt_u32 s97, 62
	s_mov_b64 s[100:101], s[42:43]
	s_mov_b64 s[98:99], s[40:41]
	s_cbranch_scc1 .Lpb19_b1
	s_add_u32 s98, s92, s95
	s_addc_u32 s99, s93, 0
	s_lshl_b64 s[100:101], s[98:99], 8
	s_add_u32 s98, s62, s100
	s_addc_u32 s99, s63, s101
	s_add_u32 s100, s70, s100
	s_addc_u32 s101, s71, s101

; #define ATT_ISSUE2(p_, st_) do { LAS unsigned char* sp_ = lds + (st_) * STG2; const int ta_ = dual ? (p_) : 2 * (p_), tb_ = dual ? (p_) : 2 * (p_) + 1; ATT_ISSUE1(u, ta_, sp_); ATT_ISSUEM(ta_, sp_ + 2 * STAGEB); \
;         if (dual || tb_ < u.ntiles) { ATT_ISSUE1(ub, tb_, sp_ + STAGEB); ATT_ISSUEM(tb_, sp_ + 2 * STAGEB + MSKB); } } while (0)
; template <int LAYER>
; __device__ __forceinline__ TileSrc tile_src(const Frame& F, const AttnUnit& u, int t, int j) {
;     ...
;         if (!u.samp) { const size_t o = ((size_t)(u.b * TP + 64 * t) * D + u.head * 128) * 2; s.k = (const char*)KA + o; s.v = (const char*)VA + o; s.ldb = D * 2; s.f32 = 0; }
;     ...
;             asm volatile("s_waitcnt vmcnt(0)" ::: "memory");
;             __builtin_amdgcn_s_barrier(); asm volatile("" ::: "memory");
;             if (p + 1 < npairs) ATT_ISSUE2(p + 1, (p + 1) & 1);
.Lpb19_b2:
	s_andn2_b64 vcc, exec, s[48:49]
	s_cbranch_vccnz .Lpb19_b3
	s_ashr_i32 s45, s44, 31
	s_lshl_b64 s[98:99], s[44:45], 12
	s_or_b64 s[100:101], s[98:99], s[6:7]
	s_add_u32 s98, s58, s100
	s_addc_u32 s99, s59, s101
	s_add_u32 s100, s52, s100
	s_addc_u32 s101, s53, s101
.Lpb19_b3:
	s_bitcmp1_b32 s96, 0
	s_cselect_b32 s45, 0x10400, 0
	s_add_i32 s61, s45, 0
	s_add_i32 s60, s61, s64
	s_add_i32 s61, s61, s66
.Lpb19_done:
	v_readlane_b32 s48, v254, 11
	s_waitcnt vmcnt(0)
	s_barrier
	s_cmp_lt_u32 s48, 4
	s_cbranch_scc1 .Lstag_3301
	s_sleep 8
	s_setprio 1
.Lstag_3301:
	s_and_b64 vcc, exec, s[46:47]
	s_cbranch_vccnz .LBB0_3316
	s_mov_b32 m0, s60
	s_nop 0
	global_load_lds_dwordx4 v248, s[2:3]
	s_add_i32 m0, s60, 0x4000
	s_nop 0
	global_load_lds_dwordx4 v249, s[4:5]
	s_mov_b32 m0, s61
	s_nop 0
	global_load_lds_dwordx4 v250, s[2:3]
	s_add_i32 s2, s94, 2
	s_add_i32 m0, s61, 0x4000
	s_cmp_ge_i32 s2, s89
	global_load_lds_dwordx4 v251, s[4:5]
	s_cselect_b64 s[2:3], -1, 0
	s_and_b64 s[2:3], s[24:25], s[2:3]
	s_and_b64 vcc, exec, s[2:3]
	s_cbranch_vccnz .LBB0_3316
	s_add_i32 m0, s60, 0x8000
	s_nop 0
	global_load_lds_dwordx4 v248, s[98:99]
	s_add_i32 m0, s60, 0xc000
	s_nop 0
	global_load_lds_dwordx4 v249, s[100:101]
	s_add_i32 m0, s61, 0x8000
	s_nop 0
	global_load_lds_dwordx4 v250, s[98:99]
	s_add_i32 m0, s61, 0xc000
	s_nop 0
	global_load_lds_dwordx4 v251, s[100:101]
